# group barriers: L1 invalidate issued at seam entry so that it overlaps the arrival/poll round trips
# speedup vs baseline: 1.0005x; 1.0005x over previous
.LBB0_629:
	s_cmp_gt_i32 s95, 7
	s_cselect_b64 s[0:1], -1, 0
	s_and_b64 s[4:5], s[4:5], s[0:1]
	s_andn2_b64 vcc, exec, s[4:5]
	s_cbranch_vccnz .LBB0_683
	s_waitcnt vmcnt(0)
	s_waitcnt vmcnt(0)
	s_barrier
	s_mov_b64 s[4:5], exec
	v_readlane_b32 s6, v246, 2
	v_readlane_b32 s7, v246, 3
	s_and_b64 s[6:7], s[4:5], s[6:7]
	s_mov_b64 exec, s[6:7]
	s_cbranch_execz .LBB0_682
	s_and_b32 s6, s2, 15
	s_lshl_b32 s6, s6, 8
	s_add_u32 s6, s92, s6
	s_addc_u32 s7, s93, 0
	s_add_u32 s6, s6, 0x53000
	s_addc_u32 s7, s7, 0
	s_add_u32 s8, s92, 0x54000
	s_addc_u32 s9, s93, 0
	v_mov_b32_e32 v1, 0
	v_mov_b32_e32 v2, 1
	buffer_inv sc1
	global_atomic_add v1, v2, s[6:7]
	s_mov_b32 s10, 0x400000
	s_movk_i32 s11, 15
	global_atomic_add v1, v2, s[8:9]
	global_load_dword v4, v1, s[8:9] offset:256 sc1
	global_load_dword v3, v1, s[6:7] sc1
	s_waitcnt vmcnt(0)
	v_readfirstlane_b32 s98, v4
	s_cmp_lg_u32 s98, 0
	s_cbranch_scc1 .Lgb6_orig
	v_cmp_lt_u32_e32 vcc, s11, v3
	s_cbranch_vccnz .Lgb6_ok
.Lgb6_poll:
	global_load_dword v3, v1, s[6:7] sc1
	s_waitcnt vmcnt(0)
	v_cmp_lt_u32_e32 vcc, s11, v3
	s_cbranch_vccnz .Lgb6_ok
	s_sleep 1
	s_sub_u32 s10, s10, 1
	s_cmp_lg_u32 s10, 0
	s_cbranch_scc1 .Lgb6_poll
.Lgb6_ok:
	s_branch .LBB0_682
.Lgb6_orig:
	s_add_i32 s6, 0, 0x22000
	v_mov_b32_e32 v1, s6
	s_waitcnt vmcnt(0) expcnt(0) lgkmcnt(0)
	ds_read_b32 v3, v1
	s_add_i32 s6, 0, 0x22004
	v_mov_b32_e32 v1, s6
	ds_read_b32 v1, v1
	s_waitcnt lgkmcnt(1)
	v_cmp_ne_u32_e32 vcc, 0, v3
	s_cbranch_vccnz .LBB0_646
	v_readlane_b32 s6, v246, 0
	v_readlane_b32 s7, v246, 1
	s_load_dwordx2 s[10:11], s[6:7], 0x4
	s_add_u32 s6, s92, 0x1000
	s_addc_u32 s7, s93, 0
	s_add_u32 s8, s92, 0x1100
	s_addc_u32 s9, s93, 0
	s_waitcnt lgkmcnt(0)
	s_mul_i32 s20, s10, s3
	s_add_u32 s10, s92, 0x1200
	s_mul_i32 s20, s20, s11
	s_addc_u32 s11, s93, 0
	s_add_u32 s12, s92, 0x1300
	s_addc_u32 s13, s93, 0
	s_mov_b32 s21, 1
	v_mov_b32_e32 v17, 0
	s_branch .LBB0_634

.LBB0_761:
	s_cmp_gt_i32 s95, 8
	s_cselect_b64 s[0:1], -1, 0
	s_and_b64 s[4:5], s[6:7], s[0:1]
	s_andn2_b64 vcc, exec, s[4:5]
	s_cbranch_vccnz .LBB0_815
	s_waitcnt vmcnt(0)
	s_waitcnt vmcnt(0)
	s_barrier
	s_mov_b64 s[4:5], exec
	v_readlane_b32 s6, v246, 2
	v_readlane_b32 s7, v246, 3
	s_and_b64 s[6:7], s[4:5], s[6:7]
	s_mov_b64 exec, s[6:7]
	s_cbranch_execz .LBB0_814
	s_cmp_lg_u32 s98, 0
	s_cbranch_scc1 .Lgb7_orig
	s_and_b32 s6, s2, 15
	s_lshl_b32 s6, s6, 8
	s_add_u32 s6, s92, s6
	s_addc_u32 s7, s93, 0
	s_add_u32 s6, s6, 0x53000
	s_addc_u32 s7, s7, 0
	s_add_u32 s8, s92, 0x54000
	s_addc_u32 s9, s93, 0
	v_mov_b32_e32 v1, 0
	v_mov_b32_e32 v2, 1
	buffer_inv sc1
	global_atomic_add v1, v2, s[6:7]
	s_mov_b32 s10, 0x400000
	s_movk_i32 s11, 31

.Lgb7_poll2:
	global_load_dword v3, v1, s[8:9] sc1
	s_waitcnt vmcnt(0)
	v_cmp_lt_u32_e32 vcc, s11, v3
	s_cbranch_vccnz .Lgb7_ok2
	s_sleep 1
	s_sub_u32 s10, s10, 1
	s_cmp_lg_u32 s10, 0
	s_cbranch_scc1 .Lgb7_poll2
.Lgb7_ok2:
	s_branch .LBB0_814
.Lgb7_orig:
	s_add_i32 s6, 0, 0x22000
	v_mov_b32_e32 v1, s6
	s_waitcnt vmcnt(0) expcnt(0) lgkmcnt(0)
	ds_read_b32 v3, v1
	s_add_i32 s6, 0, 0x22004
	v_mov_b32_e32 v1, s6
	ds_read_b32 v1, v1
	s_waitcnt lgkmcnt(1)
	v_cmp_ne_u32_e32 vcc, 0, v3
	s_cbranch_vccnz .LBB0_778
	v_readlane_b32 s6, v246, 0
	v_readlane_b32 s7, v246, 1
	s_load_dwordx2 s[10:11], s[6:7], 0x4
	s_add_u32 s6, s92, 0x1000
	s_addc_u32 s7, s93, 0
	s_add_u32 s8, s92, 0x1100
	s_addc_u32 s9, s93, 0
	s_waitcnt lgkmcnt(0)
	s_mul_i32 s20, s10, s3
	s_add_u32 s10, s92, 0x1200
	s_mul_i32 s20, s20, s11
	s_addc_u32 s11, s93, 0
	s_add_u32 s12, s92, 0x1300
	s_addc_u32 s13, s93, 0
	s_mov_b32 s21, 1
	v_mov_b32_e32 v17, 0
	s_branch .LBB0_766

.LBB0_836:
	s_cmp_gt_i32 s95, 9
	s_cselect_b64 s[0:1], -1, 0
	s_and_b64 s[4:5], s[4:5], s[0:1]
	s_andn2_b64 vcc, exec, s[4:5]
	s_cbranch_vccnz .LBB0_890
	s_waitcnt vmcnt(0)
	s_waitcnt vmcnt(0)
	s_barrier
	s_mov_b64 s[4:5], exec
	v_readlane_b32 s6, v246, 2
	v_readlane_b32 s7, v246, 3
	s_and_b64 s[6:7], s[4:5], s[6:7]
	s_mov_b64 exec, s[6:7]
	s_cbranch_execz .LBB0_889
	s_cmp_lg_u32 s98, 0
	s_cbranch_scc1 .Lgb8_orig
	s_and_b32 s6, s2, 15
	s_lshl_b32 s6, s6, 8
	s_add_u32 s6, s92, s6
	s_addc_u32 s7, s93, 0
	s_add_u32 s6, s6, 0x53000
	s_addc_u32 s7, s7, 0
	s_add_u32 s8, s92, 0x54000
	s_addc_u32 s9, s93, 0
	v_mov_b32_e32 v1, 0
	v_mov_b32_e32 v2, 1
	buffer_inv sc1
	global_atomic_add v1, v2, s[6:7]
	s_mov_b32 s10, 0x400000
	s_movk_i32 s11, 47
.Lgb8_poll:
	global_load_dword v3, v1, s[6:7] sc1
	s_waitcnt vmcnt(0)
	v_cmp_lt_u32_e32 vcc, s11, v3
	s_cbranch_vccnz .Lgb8_ok
	s_sleep 1
	s_sub_u32 s10, s10, 1
	s_cmp_lg_u32 s10, 0
	s_cbranch_scc1 .Lgb8_poll
.Lgb8_ok:
	s_branch .LBB0_889
.Lgb8_orig:
	s_add_i32 s6, 0, 0x22000
	v_mov_b32_e32 v1, s6
	s_waitcnt vmcnt(0) expcnt(0) lgkmcnt(0)
	ds_read_b32 v3, v1
	s_add_i32 s6, 0, 0x22004
	v_mov_b32_e32 v1, s6
	ds_read_b32 v1, v1
	s_waitcnt lgkmcnt(1)
	v_cmp_ne_u32_e32 vcc, 0, v3
	s_cbranch_vccnz .LBB0_853
	v_readlane_b32 s6, v246, 0
	v_readlane_b32 s7, v246, 1
	s_load_dwordx2 s[10:11], s[6:7], 0x4
	s_add_u32 s6, s92, 0x1000
	s_addc_u32 s7, s93, 0
	s_add_u32 s8, s92, 0x1100
	s_addc_u32 s9, s93, 0
	s_waitcnt lgkmcnt(0)
	s_mul_i32 s20, s10, s3
	s_add_u32 s10, s92, 0x1200
	s_mul_i32 s20, s20, s11
	s_addc_u32 s11, s93, 0
	s_add_u32 s12, s92, 0x1300
	s_addc_u32 s13, s93, 0
	s_mov_b32 s21, 1
	v_mov_b32_e32 v17, 0
	s_branch .LBB0_841
